# P0 prologue: nt (streaming) cache policy on the once-read f32 input loads (W1 and x rows)
# speedup vs baseline: 1.0030x; 1.0030x over previous
; #define LAS __attribute__((address_space(3)))
; DI unsigned pk2(float lo, float hi) { f32x2 v = {lo, hi}; bf16v2 b = __builtin_convertvector(v, bf16v2); return __builtin_bit_cast(unsigned, b); }
; DI void p0_transpose_item(const float* W, int K, int N, bf16* WT, LAS uchar* scr, int item, int lane, const float* kscale = nullptr) {
;     const int nblk = N / 64, kb = item / nblk, nb = item % nblk, k0 = 64 * kb, n0 = 64 * nb;
;     const int q = lane >> 4, c16 = lane & 15;
;     f32x4 v[16];
; #pragma unroll
;     for (int i = 0; i < 16; ++i) v[i] = *(const f32x4*)(W + (size_t)(k0 + 16 * q + i) * N + n0 + 4 * c16);
;     if (kscale) {
; #pragma unroll
;         for (int i = 0; i < 16; ++i) v[i] = v[i] * kscale[k0 + 16 * q + i]; }
; #pragma unroll
;     for (int j = 0; j < 4; ++j) { u32x4 lo, hi;
;         lo.x = pk2(v[0][j], v[1][j]); lo.y = pk2(v[2][j], v[3][j]); lo.z = pk2(v[4][j], v[5][j]); lo.w = pk2(v[6][j], v[7][j]);
;         hi.x = pk2(v[8][j], v[9][j]); hi.y = pk2(v[10][j], v[11][j]); hi.z = pk2(v[12][j], v[13][j]); hi.w = pk2(v[14][j], v[15][j]);
;         LAS uchar* p = scr + (4 * c16 + j) * TSTR + q * 32; *(LAS u32x4*)p = lo; *(LAS u32x4*)(p + 16) = hi; }
;     asm volatile("s_waitcnt lgkmcnt(0)" ::: "memory");
;     const int c = lane & 7, nr = lane >> 3;
; #pragma unroll
;     for (int r = 0; r < 8; ++r) { const int n = nr + 8 * r;
;         *(u32x4*)(WT + (size_t)(n0 + n) * K + k0 + 8 * c) = *(const LAS u32x4*)(scr + n * TSTR + c * 16); }
;     asm volatile("s_waitcnt lgkmcnt(0)" ::: "memory");
; }
.LBB0_12:
	s_mul_hi_i32 s9, s8, 0x2aaaaaab
	s_lshr_b32 s10, s9, 31
	s_ashr_i32 s9, s9, 6
	s_add_i32 s9, s9, s10
	s_lshl_b32 s10, s9, 6
	s_mulk_i32 s9, 0xa000
	s_add_i32 s12, s3, s9
	v_or_b32_e32 v9, s10, v1
	s_ashr_i32 s13, s12, 31
	s_ashr_i32 s11, s10, 31
	v_or_b32_e32 v14, 1, v9
	v_or_b32_e32 v16, 2, v9
	v_or_b32_e32 v17, 3, v9
	v_or_b32_e32 v20, 4, v9
	v_or_b32_e32 v21, 5, v9
	v_or_b32_e32 v24, 6, v9
	v_or_b32_e32 v25, 7, v9
	v_or_b32_e32 v28, 8, v9
	v_or_b32_e32 v29, 9, v9
	v_or_b32_e32 v32, 10, v9
	v_or_b32_e32 v33, 11, v9
	v_or_b32_e32 v36, 12, v9
	v_or_b32_e32 v37, 13, v9
	v_or_b32_e32 v40, 14, v9
	v_or_b32_e32 v41, 15, v9
	v_lshl_add_u64 v[10:11], s[12:13], 2, v[2:3]
	v_lshl_add_u64 v[74:75], s[10:11], 1, v[4:5]
	v_mad_i64_i32 v[12:13], s[10:11], v9, s7, v[10:11]
	v_mad_i64_i32 v[14:15], s[10:11], v14, s7, v[10:11]
	v_mad_i64_i32 v[18:19], s[10:11], v16, s7, v[10:11]
	v_mad_i64_i32 v[22:23], s[10:11], v17, s7, v[10:11]
	v_mad_i64_i32 v[26:27], s[10:11], v20, s7, v[10:11]
	v_mad_i64_i32 v[30:31], s[10:11], v21, s7, v[10:11]
	v_mad_i64_i32 v[34:35], s[10:11], v24, s7, v[10:11]
	v_mad_i64_i32 v[38:39], s[10:11], v25, s7, v[10:11]
	v_mad_i64_i32 v[42:43], s[10:11], v28, s7, v[10:11]
	v_mad_i64_i32 v[46:47], s[10:11], v29, s7, v[10:11]
	v_mad_i64_i32 v[50:51], s[10:11], v32, s7, v[10:11]
	v_mad_i64_i32 v[54:55], s[10:11], v33, s7, v[10:11]
	v_mad_i64_i32 v[58:59], s[10:11], v36, s7, v[10:11]
	v_mad_i64_i32 v[62:63], s[10:11], v37, s7, v[10:11]
	v_mad_i64_i32 v[66:67], s[10:11], v40, s7, v[10:11]
	v_mad_i64_i32 v[70:71], s[10:11], v41, s7, v[10:11]
	global_load_dwordx4 v[10:13], v[12:13], off nt
	s_nop 0
	global_load_dwordx4 v[14:17], v[14:15], off nt
	s_nop 0
	global_load_dwordx4 v[18:21], v[18:19], off nt
	s_nop 0
	global_load_dwordx4 v[22:25], v[22:23], off nt
	s_nop 0
	global_load_dwordx4 v[26:29], v[26:27], off nt
	s_nop 0
	global_load_dwordx4 v[30:33], v[30:31], off nt
	s_nop 0
	global_load_dwordx4 v[34:37], v[34:35], off nt
	s_nop 0
	global_load_dwordx4 v[38:41], v[38:39], off nt
	s_nop 0
	global_load_dwordx4 v[42:45], v[42:43], off nt
	s_nop 0
	global_load_dwordx4 v[46:49], v[46:47], off nt
	s_nop 0
	global_load_dwordx4 v[50:53], v[50:51], off nt
	s_nop 0
	global_load_dwordx4 v[54:57], v[54:55], off nt
	s_nop 0
	global_load_dwordx4 v[58:61], v[58:59], off nt
	s_nop 0
	global_load_dwordx4 v[62:65], v[62:63], off nt
	s_nop 0
	global_load_dwordx4 v[66:69], v[66:67], off nt
	s_nop 0
	global_load_dwordx4 v[70:73], v[70:71], off nt
	v_add_u32_e32 v76, s12, v6
	v_ashrrev_i32_e32 v77, 31, v76
	v_add_u32_e32 v78, 8, v76
	v_add_u32_e32 v80, 16, v76
	v_add_u32_e32 v82, 24, v76
	v_add_u32_e32 v84, 32, v76
	v_add_u32_e32 v86, 40, v76
	v_add_u32_e32 v88, 48, v76
	v_add_u32_e32 v90, 56, v76
	v_lshlrev_b64 v[76:77], 13, v[76:77]
	v_ashrrev_i32_e32 v79, 31, v78
	v_ashrrev_i32_e32 v81, 31, v80
	v_ashrrev_i32_e32 v83, 31, v82
	v_ashrrev_i32_e32 v85, 31, v84
	v_ashrrev_i32_e32 v87, 31, v86
	v_ashrrev_i32_e32 v89, 31, v88
	v_ashrrev_i32_e32 v91, 31, v90
	v_lshl_add_u64 v[92:93], v[74:75], 0, v[76:77]
	v_lshlrev_b64 v[76:77], 13, v[78:79]
	v_lshlrev_b64 v[78:79], 13, v[80:81]
	v_lshlrev_b64 v[80:81], 13, v[82:83]
	v_lshlrev_b64 v[82:83], 13, v[84:85]
	v_lshlrev_b64 v[84:85], 13, v[86:87]
	v_lshlrev_b64 v[86:87], 13, v[88:89]
	v_lshlrev_b64 v[88:89], 13, v[90:91]
	v_lshl_add_u64 v[90:91], v[74:75], 0, v[76:77]
	v_lshl_add_u64 v[94:95], v[74:75], 0, v[78:79]
	v_lshl_add_u64 v[96:97], v[74:75], 0, v[80:81]
	v_lshl_add_u64 v[82:83], v[74:75], 0, v[82:83]
	v_lshl_add_u64 v[84:85], v[74:75], 0, v[84:85]
	v_lshl_add_u64 v[86:87], v[74:75], 0, v[86:87]
	v_lshl_add_u64 v[88:89], v[74:75], 0, v[88:89]
	s_add_i32 s8, s8, s6
	s_add_i32 s3, s3, s5
	s_cmpk_gt_i32 s8, 0x5fff
	s_waitcnt vmcnt(14)
	v_cvt_pk_bf16_f32 v10, v10, v14
	v_cvt_pk_bf16_f32 v14, v11, v15
	v_cvt_pk_bf16_f32 v74, v12, v16
	v_cvt_pk_bf16_f32 v78, v13, v17
	s_waitcnt vmcnt(12)
	v_cvt_pk_bf16_f32 v11, v18, v22
	s_waitcnt vmcnt(10)
	v_cvt_pk_bf16_f32 v12, v26, v30
	s_waitcnt vmcnt(8)
	v_cvt_pk_bf16_f32 v13, v34, v38
	v_cvt_pk_bf16_f32 v15, v19, v23
	v_cvt_pk_bf16_f32 v75, v20, v24
	v_cvt_pk_bf16_f32 v79, v21, v25
	v_cvt_pk_bf16_f32 v16, v27, v31
	v_cvt_pk_bf16_f32 v76, v28, v32
	v_cvt_pk_bf16_f32 v80, v29, v33
	s_waitcnt vmcnt(6)
	v_cvt_pk_bf16_f32 v18, v42, v46
	v_cvt_pk_bf16_f32 v17, v35, v39
	v_cvt_pk_bf16_f32 v77, v36, v40
	v_cvt_pk_bf16_f32 v81, v37, v41
	v_cvt_pk_bf16_f32 v22, v43, v47
	v_cvt_pk_bf16_f32 v26, v44, v48
	v_cvt_pk_bf16_f32 v30, v45, v49
	s_waitcnt vmcnt(4)
	v_cvt_pk_bf16_f32 v19, v50, v54
	v_cvt_pk_bf16_f32 v23, v51, v55
	v_cvt_pk_bf16_f32 v27, v52, v56
	v_cvt_pk_bf16_f32 v31, v53, v57
	s_waitcnt vmcnt(2)
	v_cvt_pk_bf16_f32 v20, v58, v62
	v_cvt_pk_bf16_f32 v24, v59, v63
	v_cvt_pk_bf16_f32 v28, v60, v64
	v_cvt_pk_bf16_f32 v32, v61, v65
	s_waitcnt vmcnt(0)
	v_cvt_pk_bf16_f32 v21, v66, v70
	v_cvt_pk_bf16_f32 v25, v67, v71
	v_cvt_pk_bf16_f32 v29, v68, v72
	v_cvt_pk_bf16_f32 v33, v69, v73
	ds_write_b128 v7, v[10:13]
	ds_write_b128 v7, v[18:21] offset:16
	ds_write_b128 v7, v[14:17] offset:144
	ds_write_b128 v7, v[22:25] offset:160
	ds_write_b128 v7, v[74:77] offset:288
	ds_write_b128 v7, v[26:29] offset:304
	ds_write_b128 v7, v[78:81] offset:432
	ds_write_b128 v7, v[30:33] offset:448
	s_waitcnt lgkmcnt(0)
	ds_read_b128 v[10:13], v8
	ds_read_b128 v[14:17], v8 offset:1152
	ds_read_b128 v[18:21], v8 offset:2304
	ds_read_b128 v[22:25], v8 offset:3456
	ds_read_b128 v[26:29], v8 offset:4608
	ds_read_b128 v[30:33], v8 offset:5760
	ds_read_b128 v[34:37], v8 offset:6912
	ds_read_b128 v[38:41], v8 offset:8064
	s_waitcnt lgkmcnt(7)
	global_store_dwordx4 v[92:93], v[10:13], off
	s_waitcnt lgkmcnt(6)
	global_store_dwordx4 v[90:91], v[14:17], off
	s_waitcnt lgkmcnt(5)
	global_store_dwordx4 v[94:95], v[18:21], off
	s_waitcnt lgkmcnt(4)
	global_store_dwordx4 v[96:97], v[22:25], off
	s_waitcnt lgkmcnt(3)
	global_store_dwordx4 v[82:83], v[26:29], off
	s_waitcnt lgkmcnt(2)
	global_store_dwordx4 v[84:85], v[30:33], off
	s_waitcnt lgkmcnt(1)
	global_store_dwordx4 v[86:87], v[34:37], off
	s_waitcnt lgkmcnt(0)
	global_store_dwordx4 v[88:89], v[38:41], off
	s_waitcnt lgkmcnt(0)
	s_cbranch_scc0 .LBB0_12

; DI unsigned pk2(float lo, float hi) { f32x2 v = {lo, hi}; bf16v2 b = __builtin_convertvector(v, bf16v2); return __builtin_bit_cast(unsigned, b); }
; DI void rms_row_to_bf16(const float* xrow, const float* w, bf16* orow, int lane) {
;     const f32x4* xr = (const f32x4*)xrow + lane; const f32x4* wr = (const f32x4*)w + lane;
;     f32x4 v[16]; float s = 0.f;
; #pragma unroll
;     for (int j = 0; j < 16; ++j) { v[j] = xr[64 * j]; s += (v[j].x * v[j].x + v[j].y * v[j].y) + (v[j].z * v[j].z + v[j].w * v[j].w); }
;     const float rstd = __builtin_amdgcn_rsqf(wave_sum(s) * (1.f / 4096.f) + EPS);
;     u32x2* o8 = (u32x2*)orow + lane;
; #pragma unroll
;     for (int j = 0; j < 16; ++j) { const f32x4 ww = wr[64 * j]; u32x2 p; p.x = pk2(v[j].x * rstd * ww.x, v[j].y * rstd * ww.y); p.y = pk2(v[j].z * rstd * ww.z, v[j].w * rstd * ww.w); o8[64 * j] = p; }
; }
.LBB0_18:
	global_load_dwordx4 v[14:17], v[88:89], off nt
	global_load_dwordx4 v[10:13], v[88:89], off offset:1024 nt
	global_load_dwordx4 v[6:9], v[88:89], off offset:2048 nt
	global_load_dwordx4 v[2:5], v[88:89], off offset:3072 nt
	v_add_co_u32_e32 v18, vcc, s3, v88
	s_add_i32 s4, s4, s6
	s_nop 0
	v_addc_co_u32_e32 v19, vcc, 0, v89, vcc
	v_add_co_u32_e32 v20, vcc, s5, v88
	s_cmpk_lt_i32 s4, 0x4000
	s_nop 0
	v_addc_co_u32_e32 v21, vcc, 0, v89, vcc
	v_add_co_u32_e32 v22, vcc, s7, v88
	s_waitcnt vmcnt(3)
	v_pk_mul_f32 v[108:109], v[16:17], v[16:17]
	v_addc_co_u32_e32 v23, vcc, 0, v89, vcc
	global_load_dwordx4 v[100:103], v[62:63], off
	global_load_dwordx4 v[104:107], v[20:21], off offset:-4096 nt
	global_load_dwordx4 v[54:57], v[18:19], off offset:2048 nt
	global_load_dwordx4 v[58:61], v[18:19], off offset:1024 nt
	global_load_dwordx4 v[50:53], v[18:19], off offset:3072 nt
	global_load_dwordx4 v[42:45], v[20:21], off offset:1024 nt
	global_load_dwordx4 v[46:49], v[20:21], off nt
	global_load_dwordx4 v[38:41], v[20:21], off offset:2048 nt
	global_load_dwordx4 v[30:33], v[22:23], off nt
	global_load_dwordx4 v[34:37], v[20:21], off offset:3072 nt
	global_load_dwordx4 v[26:29], v[22:23], off offset:1024 nt
	s_nop 0
	global_load_dwordx4 v[18:21], v[22:23], off offset:3072 nt
	s_nop 0
	global_load_dwordx4 v[22:25], v[22:23], off offset:2048 nt
	v_pk_mul_f32 v[110:111], v[14:15], v[14:15]
	s_waitcnt vmcnt(15)
	v_pk_mul_f32 v[112:113], v[12:13], v[12:13]
	v_pk_mul_f32 v[114:115], v[10:11], v[10:11]
	v_pk_mov_b32 v[118:119], v[110:111], v[108:109] op_sel:[1,0]
	v_mov_b32_e32 v111, v109
	v_pk_mov_b32 v[108:109], v[114:115], v[112:113] op_sel:[1,0]
	v_mov_b32_e32 v115, v113
	s_waitcnt vmcnt(14)
	v_mul_f32_e32 v92, v7, v7
	v_mul_f32_e32 v116, v9, v9
	v_pk_add_f32 v[110:111], v[118:119], v[110:111]
	v_pk_add_f32 v[108:109], v[108:109], v[114:115]
	s_waitcnt vmcnt(13)
	v_mul_f32_e32 v99, v2, v2
	v_mul_f32_e32 v149, v3, v3
	v_mul_f32_e32 v125, v4, v4
	v_mul_f32_e32 v131, v5, v5
	v_pk_fma_f32 v[112:113], v[6:7], v[6:7], v[92:93] op_sel_hi:[1,1,0]
	v_pk_fma_f32 v[116:117], v[8:9], v[8:9], v[116:117] op_sel_hi:[1,1,0]
	v_pk_add_f32 v[110:111], v[110:111], v[110:111] op_sel:[0,1] op_sel_hi:[1,0]
	v_pk_add_f32 v[108:109], v[108:109], v[108:109] op_sel:[0,1] op_sel_hi:[1,0]
	v_mov_b32_e32 v113, v125
	v_mov_b32_e32 v117, v131
	v_mov_b32_e32 v111, v99
	v_mov_b32_e32 v109, v149
	v_pk_add_f32 v[112:113], v[112:113], v[116:117]
	v_pk_add_f32 v[108:109], v[110:111], v[108:109]
	v_lshl_add_u64 v[88:89], v[88:89], 0, s[8:9]
	v_pk_add_f32 v[108:109], v[108:109], v[112:113]
	s_waitcnt vmcnt(11)
	v_pk_mul_f32 v[120:121], v[106:107], v[106:107]
	v_pk_mul_f32 v[122:123], v[104:105], v[104:105]
	s_waitcnt vmcnt(9)
	v_mul_f32_e32 v92, v59, v59
	v_pk_mov_b32 v[114:115], v[122:123], v[120:121] op_sel:[1,0]
	v_mov_b32_e32 v123, v121
	v_mul_f32_e32 v124, v61, v61
	v_pk_add_f32 v[114:115], v[114:115], v[122:123]
	v_mul_f32_e32 v150, v54, v54
	v_mul_f32_e32 v151, v55, v55
	v_mul_f32_e32 v152, v56, v56
	v_mul_f32_e32 v153, v57, v57
	v_pk_fma_f32 v[118:119], v[58:59], v[58:59], v[92:93] op_sel_hi:[1,1,0]
	v_pk_fma_f32 v[120:121], v[60:61], v[60:61], v[124:125] op_sel_hi:[1,1,0]
	v_pk_add_f32 v[114:115], v[114:115], v[114:115] op_sel:[0,1] op_sel_hi:[1,0]
	v_pk_add_f32 v[108:109], v[108:109], v[108:109] op_sel:[0,1] op_sel_hi:[1,0]
	s_waitcnt vmcnt(8)
	v_pk_mul_f32 v[126:127], v[52:53], v[52:53]
	v_pk_mul_f32 v[128:129], v[50:51], v[50:51]
	v_mov_b32_e32 v119, v152
	v_mov_b32_e32 v121, v153
	v_mov_b32_e32 v115, v151
	v_mov_b32_e32 v109, v150
	v_pk_mov_b32 v[124:125], v[128:129], v[126:127] op_sel:[1,0]
	v_mov_b32_e32 v129, v127
	v_pk_add_f32 v[118:119], v[118:119], v[120:121]
	v_pk_add_f32 v[108:109], v[108:109], v[114:115]
	s_waitcnt vmcnt(6)
	v_mul_f32_e32 v130, v47, v47
	v_mul_f32_e32 v132, v49, v49
	v_pk_add_f32 v[116:117], v[124:125], v[128:129]
	v_pk_add_f32 v[108:109], v[108:109], v[118:119]
	v_mul_f32_e32 v154, v42, v42
	v_mul_f32_e32 v155, v43, v43
	v_mul_f32_e32 v156, v44, v44
	v_mul_f32_e32 v157, v45, v45
	v_pk_fma_f32 v[126:127], v[46:47], v[46:47], v[130:131] op_sel_hi:[1,1,0]
	v_pk_fma_f32 v[130:131], v[48:49], v[48:49], v[132:133] op_sel_hi:[1,1,0]
	v_pk_add_f32 v[116:117], v[116:117], v[116:117] op_sel:[0,1] op_sel_hi:[1,0]
	v_pk_add_f32 v[108:109], v[108:109], v[108:109] op_sel:[0,1] op_sel_hi:[1,0]
	s_waitcnt vmcnt(5)
	v_pk_mul_f32 v[134:135], v[40:41], v[40:41]
	v_pk_mul_f32 v[136:137], v[38:39], v[38:39]
	v_mov_b32_e32 v127, v156
	v_mov_b32_e32 v131, v157
	v_mov_b32_e32 v117, v155
	v_mov_b32_e32 v109, v154
	v_pk_mov_b32 v[132:133], v[136:137], v[134:135] op_sel:[1,0]
	v_mov_b32_e32 v137, v135
	v_pk_add_f32 v[120:121], v[126:127], v[130:131]
	v_pk_add_f32 v[108:109], v[108:109], v[116:117]
	s_waitcnt vmcnt(3)
	v_mul_f32_e32 v138, v35, v35
	v_mul_f32_e32 v140, v37, v37
	v_pk_add_f32 v[122:123], v[132:133], v[136:137]
	v_pk_add_f32 v[108:109], v[108:109], v[120:121]
	v_mul_f32_e32 v158, v30, v30
	v_mul_f32_e32 v159, v31, v31
	v_mul_f32_e32 v160, v32, v32
	v_mul_f32_e32 v161, v33, v33
	v_pk_fma_f32 v[134:135], v[34:35], v[34:35], v[138:139] op_sel_hi:[1,1,0]
	v_pk_fma_f32 v[138:139], v[36:37], v[36:37], v[140:141] op_sel_hi:[1,1,0]
	v_pk_add_f32 v[122:123], v[122:123], v[122:123] op_sel:[0,1] op_sel_hi:[1,0]
	v_pk_add_f32 v[108:109], v[108:109], v[108:109] op_sel:[0,1] op_sel_hi:[1,0]
	s_waitcnt vmcnt(2)
	v_pk_mul_f32 v[142:143], v[28:29], v[28:29]
	v_pk_mul_f32 v[144:145], v[26:27], v[26:27]
	v_mov_b32_e32 v135, v160
	v_mov_b32_e32 v139, v161
	v_mov_b32_e32 v123, v159
	v_mov_b32_e32 v109, v158
	v_pk_mov_b32 v[140:141], v[144:145], v[142:143] op_sel:[1,0]
	v_mov_b32_e32 v145, v143
	v_pk_add_f32 v[126:127], v[134:135], v[138:139]
	v_pk_add_f32 v[108:109], v[108:109], v[122:123]
	s_waitcnt vmcnt(0)
; DI unsigned pk2(float lo, float hi) { f32x2 v = {lo, hi}; bf16v2 b = __builtin_convertvector(v, bf16v2); return __builtin_bit_cast(unsigned, b); }
; DI float wave_sum(float v) {
; #pragma unroll
;     for (int o = 1; o < 64; o <<= 1) v += __shfl_xor(v, o);
;     return v;
; DI void rms_row_to_bf16(const float* xrow, const float* w, bf16* orow, int lane) {
;     ...
;     for (int j = 0; j < 16; ++j) { v[j] = xr[64 * j]; s += (v[j].x * v[j].x + v[j].y * v[j].y) + (v[j].z * v[j].z + v[j].w * v[j].w); }
;     const float rstd = __builtin_amdgcn_rsqf(wave_sum(s) * (1.f / 4096.f) + EPS);
;     u32x2* o8 = (u32x2*)orow + lane;
; #pragma unroll
;     for (int j = 0; j < 16; ++j) { const f32x4 ww = wr[64 * j]; u32x2 p; p.x = pk2(v[j].x * rstd * ww.x, v[j].y * rstd * ww.y); p.y = pk2(v[j].z * rstd * ww.z, v[j].w * rstd * ww.w); o8[64 * j] = p; }
	v_mul_f32_e32 v146, v23, v23
	v_mul_f32_e32 v148, v25, v25
	v_pk_add_f32 v[124:125], v[140:141], v[144:145]
	v_pk_add_f32 v[108:109], v[108:109], v[126:127]
	v_mul_f32_e32 v162, v18, v18
	v_mul_f32_e32 v163, v19, v19
	v_mul_f32_e32 v164, v20, v20
	v_mul_f32_e32 v165, v21, v21
	v_pk_fma_f32 v[142:143], v[22:23], v[22:23], v[146:147] op_sel_hi:[1,1,0]
	v_pk_fma_f32 v[146:147], v[24:25], v[24:25], v[148:149] op_sel_hi:[1,1,0]
	v_pk_add_f32 v[124:125], v[124:125], v[124:125] op_sel:[0,1] op_sel_hi:[1,0]
	v_pk_add_f32 v[108:109], v[108:109], v[108:109] op_sel:[0,1] op_sel_hi:[1,0]
	v_mov_b32_e32 v143, v164
	v_mov_b32_e32 v147, v165
	v_mov_b32_e32 v125, v163
	v_mov_b32_e32 v109, v162
	v_pk_add_f32 v[128:129], v[142:143], v[146:147]
	v_pk_add_f32 v[108:109], v[108:109], v[124:125]
	s_nop 0
	v_pk_add_f32 v[108:109], v[108:109], v[128:129]
	s_nop 0
	v_add_f32_e32 v92, v108, v109
	ds_bpermute_b32 v99, v1, v92
	s_waitcnt lgkmcnt(0)
	v_add_f32_e32 v92, v92, v99
	ds_bpermute_b32 v99, v93, v92
	s_waitcnt lgkmcnt(0)
	v_add_f32_e32 v92, v92, v99
	ds_bpermute_b32 v99, v94, v92
	s_waitcnt lgkmcnt(0)
	v_add_f32_e32 v92, v92, v99
	ds_bpermute_b32 v99, v95, v92
	s_waitcnt lgkmcnt(0)
	v_add_f32_e32 v92, v92, v99
	ds_bpermute_b32 v99, v96, v92
	s_waitcnt lgkmcnt(0)
	v_add_f32_e32 v92, v92, v99
	ds_bpermute_b32 v99, v97, v92
	s_waitcnt lgkmcnt(0)
	v_add_f32_e32 v92, v92, v99
	v_fmamk_f32 v92, v92, 0x39800000, v98
	v_rsq_f32_e32 v92, v92
	s_nop 0
	v_pk_mul_f32 v[14:15], v[14:15], v[92:93] op_sel_hi:[1,0]
	v_pk_mul_f32 v[16:17], v[16:17], v[92:93] op_sel_hi:[1,0]
	v_pk_mul_f32 v[14:15], v[100:101], v[14:15]
	v_pk_mul_f32 v[16:17], v[102:103], v[16:17]
	v_cvt_pk_bf16_f32 v14, v14, v15
	v_cvt_pk_bf16_f32 v15, v16, v17
	global_store_dwordx2 v[90:91], v[14:15], off
	global_load_dwordx4 v[14:17], v[62:63], off offset:1024
	v_pk_mul_f32 v[10:11], v[10:11], v[92:93] op_sel_hi:[1,0]
	v_pk_mul_f32 v[12:13], v[12:13], v[92:93] op_sel_hi:[1,0]
	v_pk_mul_f32 v[6:7], v[6:7], v[92:93] op_sel_hi:[1,0]
	v_pk_mul_f32 v[8:9], v[8:9], v[92:93] op_sel_hi:[1,0]
	v_pk_mul_f32 v[2:3], v[2:3], v[92:93] op_sel_hi:[1,0]
	v_pk_mul_f32 v[4:5], v[4:5], v[92:93] op_sel_hi:[1,0]
	s_waitcnt vmcnt(0)
	v_pk_mul_f32 v[10:11], v[14:15], v[10:11]
	v_pk_mul_f32 v[12:13], v[16:17], v[12:13]
	v_cvt_pk_bf16_f32 v10, v10, v11
	v_cvt_pk_bf16_f32 v11, v12, v13
	global_store_dwordx2 v[90:91], v[10:11], off offset:512
	global_load_dwordx4 v[10:13], v[62:63], off offset:2048
	s_waitcnt vmcnt(0)
	v_pk_mul_f32 v[6:7], v[10:11], v[6:7]
	v_pk_mul_f32 v[8:9], v[12:13], v[8:9]
	v_cvt_pk_bf16_f32 v6, v6, v7
	v_cvt_pk_bf16_f32 v7, v8, v9
	global_store_dwordx2 v[90:91], v[6:7], off offset:1024
	global_load_dwordx4 v[6:9], v[62:63], off offset:3072
	v_pk_mul_f32 v[10:11], v[48:49], v[92:93] op_sel_hi:[1,0]
	s_waitcnt vmcnt(0)
	v_pk_mul_f32 v[2:3], v[6:7], v[2:3]
	v_pk_mul_f32 v[4:5], v[8:9], v[4:5]
	v_cvt_pk_bf16_f32 v2, v2, v3
	v_cvt_pk_bf16_f32 v3, v4, v5
	global_store_dwordx2 v[90:91], v[2:3], off offset:1536
	global_load_dwordx4 v[2:5], v[64:65], off
	v_pk_mul_f32 v[6:7], v[104:105], v[92:93] op_sel_hi:[1,0]
	v_pk_mul_f32 v[8:9], v[106:107], v[92:93] op_sel_hi:[1,0]
	s_waitcnt vmcnt(0)
	v_pk_mul_f32 v[2:3], v[6:7], v[2:3]
	v_pk_mul_f32 v[4:5], v[8:9], v[4:5]
	v_cvt_pk_bf16_f32 v2, v2, v3
	v_cvt_pk_bf16_f32 v3, v4, v5
	global_store_dwordx2 v[90:91], v[2:3], off offset:2048
	global_load_dwordx4 v[2:5], v[66:67], off
	v_pk_mul_f32 v[6:7], v[58:59], v[92:93] op_sel_hi:[1,0]
	v_pk_mul_f32 v[8:9], v[60:61], v[92:93] op_sel_hi:[1,0]
	s_waitcnt vmcnt(0)
	v_pk_mul_f32 v[2:3], v[6:7], v[2:3]
	v_pk_mul_f32 v[4:5], v[8:9], v[4:5]
	v_cvt_pk_bf16_f32 v2, v2, v3
	v_cvt_pk_bf16_f32 v3, v4, v5
	global_store_dwordx2 v[90:91], v[2:3], off offset:2560
	global_load_dwordx4 v[2:5], v[68:69], off
	v_pk_mul_f32 v[6:7], v[54:55], v[92:93] op_sel_hi:[1,0]
	v_pk_mul_f32 v[8:9], v[56:57], v[92:93] op_sel_hi:[1,0]
	s_waitcnt vmcnt(0)
; DI unsigned pk2(float lo, float hi) { f32x2 v = {lo, hi}; bf16v2 b = __builtin_convertvector(v, bf16v2); return __builtin_bit_cast(unsigned, b); }
; DI void rms_row_to_bf16(const float* xrow, const float* w, bf16* orow, int lane) {
;     ...
; #pragma unroll
;     for (int j = 0; j < 16; ++j) { const f32x4 ww = wr[64 * j]; u32x2 p; p.x = pk2(v[j].x * rstd * ww.x, v[j].y * rstd * ww.y); p.y = pk2(v[j].z * rstd * ww.z, v[j].w * rstd * ww.w); o8[64 * j] = p; }
	v_pk_mul_f32 v[2:3], v[6:7], v[2:3]
	v_pk_mul_f32 v[4:5], v[8:9], v[4:5]
	v_cvt_pk_bf16_f32 v2, v2, v3
	v_cvt_pk_bf16_f32 v3, v4, v5
	global_store_dwordx2 v[90:91], v[2:3], off offset:3072
	global_load_dwordx4 v[2:5], v[70:71], off
	v_pk_mul_f32 v[6:7], v[50:51], v[92:93] op_sel_hi:[1,0]
	v_pk_mul_f32 v[8:9], v[52:53], v[92:93] op_sel_hi:[1,0]
	s_waitcnt vmcnt(0)
	v_pk_mul_f32 v[2:3], v[6:7], v[2:3]
	v_pk_mul_f32 v[4:5], v[8:9], v[4:5]
	v_cvt_pk_bf16_f32 v2, v2, v3
	v_cvt_pk_bf16_f32 v3, v4, v5
	global_store_dwordx2 v[90:91], v[2:3], off offset:3584
	global_load_dwordx4 v[2:5], v[72:73], off
	v_pk_mul_f32 v[8:9], v[46:47], v[92:93] op_sel_hi:[1,0]
	v_add_co_u32_e32 v6, vcc, s3, v90
	s_waitcnt vmcnt(0)
	v_pk_mul_f32 v[2:3], v[8:9], v[2:3]
	v_pk_mul_f32 v[4:5], v[10:11], v[4:5]
	v_addc_co_u32_e32 v7, vcc, 0, v91, vcc
	v_cvt_pk_bf16_f32 v2, v2, v3
	v_cvt_pk_bf16_f32 v3, v4, v5
	global_store_dwordx2 v[6:7], v[2:3], off
	global_load_dwordx4 v[2:5], v[74:75], off
	v_pk_mul_f32 v[8:9], v[42:43], v[92:93] op_sel_hi:[1,0]
	v_pk_mul_f32 v[10:11], v[44:45], v[92:93] op_sel_hi:[1,0]
	v_lshl_add_u64 v[90:91], v[90:91], 0, s[10:11]
	s_waitcnt vmcnt(0)
	v_pk_mul_f32 v[2:3], v[8:9], v[2:3]
	v_pk_mul_f32 v[4:5], v[10:11], v[4:5]
	v_cvt_pk_bf16_f32 v2, v2, v3
	v_cvt_pk_bf16_f32 v3, v4, v5
	global_store_dwordx2 v[6:7], v[2:3], off offset:512
	global_load_dwordx4 v[2:5], v[76:77], off
	v_pk_mul_f32 v[8:9], v[38:39], v[92:93] op_sel_hi:[1,0]
	v_pk_mul_f32 v[10:11], v[40:41], v[92:93] op_sel_hi:[1,0]
	s_waitcnt vmcnt(0)
	v_pk_mul_f32 v[2:3], v[8:9], v[2:3]
	v_pk_mul_f32 v[4:5], v[10:11], v[4:5]
	v_cvt_pk_bf16_f32 v2, v2, v3
	v_cvt_pk_bf16_f32 v3, v4, v5
	global_store_dwordx2 v[6:7], v[2:3], off offset:1024
	global_load_dwordx4 v[2:5], v[78:79], off
	v_pk_mul_f32 v[8:9], v[34:35], v[92:93] op_sel_hi:[1,0]
	v_pk_mul_f32 v[10:11], v[36:37], v[92:93] op_sel_hi:[1,0]
	s_waitcnt vmcnt(0)
	v_pk_mul_f32 v[2:3], v[8:9], v[2:3]
	v_pk_mul_f32 v[4:5], v[10:11], v[4:5]
	v_cvt_pk_bf16_f32 v2, v2, v3
	v_cvt_pk_bf16_f32 v3, v4, v5
	global_store_dwordx2 v[6:7], v[2:3], off offset:1536
	global_load_dwordx4 v[2:5], v[80:81], off
	v_pk_mul_f32 v[8:9], v[30:31], v[92:93] op_sel_hi:[1,0]
	v_pk_mul_f32 v[10:11], v[32:33], v[92:93] op_sel_hi:[1,0]
	s_waitcnt vmcnt(0)
	v_pk_mul_f32 v[2:3], v[8:9], v[2:3]
	v_pk_mul_f32 v[4:5], v[10:11], v[4:5]
	v_cvt_pk_bf16_f32 v2, v2, v3
	v_cvt_pk_bf16_f32 v3, v4, v5
	global_store_dwordx2 v[6:7], v[2:3], off offset:2048
	global_load_dwordx4 v[2:5], v[82:83], off
	v_pk_mul_f32 v[8:9], v[26:27], v[92:93] op_sel_hi:[1,0]
	v_pk_mul_f32 v[10:11], v[28:29], v[92:93] op_sel_hi:[1,0]
	s_waitcnt vmcnt(0)
	v_pk_mul_f32 v[2:3], v[8:9], v[2:3]
	v_pk_mul_f32 v[4:5], v[10:11], v[4:5]
	v_cvt_pk_bf16_f32 v2, v2, v3
	v_cvt_pk_bf16_f32 v3, v4, v5
	global_store_dwordx2 v[6:7], v[2:3], off offset:2560
	global_load_dwordx4 v[2:5], v[84:85], off
	v_pk_mul_f32 v[8:9], v[22:23], v[92:93] op_sel_hi:[1,0]
	v_pk_mul_f32 v[10:11], v[24:25], v[92:93] op_sel_hi:[1,0]
	s_waitcnt vmcnt(0)
	v_pk_mul_f32 v[2:3], v[8:9], v[2:3]
	v_pk_mul_f32 v[4:5], v[10:11], v[4:5]
	v_cvt_pk_bf16_f32 v2, v2, v3
	v_cvt_pk_bf16_f32 v3, v4, v5
	global_store_dwordx2 v[6:7], v[2:3], off offset:3072
	global_load_dwordx4 v[2:5], v[86:87], off
	v_pk_mul_f32 v[8:9], v[18:19], v[92:93] op_sel_hi:[1,0]
	v_pk_mul_f32 v[10:11], v[20:21], v[92:93] op_sel_hi:[1,0]
	s_waitcnt vmcnt(0)
	v_pk_mul_f32 v[2:3], v[8:9], v[2:3]
	v_pk_mul_f32 v[4:5], v[10:11], v[4:5]
	v_cvt_pk_bf16_f32 v2, v2, v3
	v_cvt_pk_bf16_f32 v3, v4, v5
	global_store_dwordx2 v[6:7], v[2:3], off offset:3584
	s_cbranch_scc1 .LBB0_18
